# phase dispatch: PROG[pc] computed with SALU compares instead of a vector byte load + vmcnt(0) after every grid barrier
# speedup vs baseline: 1.0154x; 1.0059x over previous
; #define LAUNDER_S(x) asm volatile("" : "+s"(x))
; __global__ void __launch_bounds__(512, 2) fwd_mega(Params p) {
;     ...
;     for (int pc = 0; pc < NPROG * 2; ++pc) {
;         const int l = (pc >= NPROG) ? 1 : 0;
;         const int sl = PROG[pc - NPROG * l];
;         const int step = 19 * l + sl;
;         if (l == 1 && sl == 0) continue;
;         unsigned char* ws = p.ws; LAUNDER_S(ws);
;             const int G = gridDim.x; int bid = blockIdx.x; LAUNDER_S(bid);
;         const float* x = p.in[0];
;         h16* hbuf = (h16*)p.out;
;         h16* XN = (h16*)(ws + R1);
;         h16* HID = (h16*)(ws + R0);
;         h16* Pda = (h16*)(ws + R0);
;         h16* Pdn = (h16*)(ws + R0);
;         h16* OB = (h16*)(ws + R2);
;         h16* GATE_A = (h16*)(ws + R3 + 64 * MiB); h16* GATE_B = (h16*)(ws + R3);
;         h16* Tg = (h16*)(ws + R3_T); h16* QKg = (h16*)(ws + R3_QK); h16* HALO = (h16*)(ws + R3_HALO);
;         h16* Wdn = (h16*)(ws + R3_WDN); h16* Wda = (h16*)(ws + R3_WDA);
;         const size_t ffoff = (l == 1 && (sl == 1 || sl == 2)) ? 32 * MiB : 0;
;         h16* W1t = (h16*)(ws + R3_W1 + ffoff); h16* W2t = (h16*)(ws + R3_W2 + ffoff);
;         h16* Wg = (h16*)(ws + R4_WG); h16* Wa = (h16*)(ws + R4_WA); h16* Wb = (h16*)(ws + R4_WB); h16* Wo = (h16*)(ws + R4_WO);
;         float* MOD = (float*)(ws + R4_MOD); float* BD = (float*)(ws + R4_BD); float* LSE = (float*)(ws + R4_LSE);
;         float* GC = (float*)(ws + R4_GC); float* BETA = (float*)(ws + R4_BETA);
;         const float* modl = MOD + (unsigned)l * 8 * 9216;
;         const bool first = (step == 0) || (step == 2);
;         const float* hin32 = first ? x : (const float*)nullptr;
.LBB0_92:
	s_cmp_gt_u32 s33, 14
	s_cselect_b64 s[20:21], -1, 0
	s_and_b64 s[0:1], s[20:21], exec
	s_cselect_b32 s0, -15, 0
	s_add_i32 s2, s0, s33
	s_ashr_i32 s3, s2, 31
	s_mov_b32 s3, s2
	s_cmp_gt_u32 s2, 2
	s_addc_u32 s3, s3, 0
	s_cmp_gt_u32 s2, 7
	s_addc_u32 s3, s3, 0
	s_cmp_gt_u32 s2, 9
	s_addc_u32 s3, s3, 0
	s_cmp_gt_u32 s2, 12
	s_addc_u32 s3, s3, 0
	s_and_b32 s2, 0xffff, s3
	s_cmp_lg_u32 s2, 0
	s_cselect_b64 s[0:1], -1, 0
	s_cmp_eq_u32 s2, 0
	s_cselect_b64 s[4:5], -1, 0
	s_and_b64 s[4:5], s[20:21], s[4:5]
	s_and_b64 vcc, exec, s[4:5]
	s_cbranch_vccnz .LBB0_91
	s_and_b32 s6, s3, 0xff
	s_and_b64 s[4:5], s[20:21], exec
	s_cselect_b32 s2, 19, 0
	v_writelane_b32 v254, s6, 63
	s_add_i32 s2, s2, s6
	v_readlane_b32 s4, v253, 0
	v_readlane_b32 s18, v253, 14
	v_readlane_b32 s19, v253, 15
	s_mov_b64 s[86:87], s[18:19]
	s_add_u32 s84, s86, 0x10000000
	s_addc_u32 s85, s87, 0
	v_readlane_b32 s5, v253, 1
	s_add_u32 s4, s86, 0x1ba00000
	v_writelane_b32 v255, s2, 0
	s_addc_u32 s5, s87, 0
	v_writelane_b32 v255, s4, 1
	v_readlane_b32 s8, v253, 4
	v_readlane_b32 s6, v253, 2
	v_writelane_b32 v255, s5, 2
	s_add_u32 s4, s86, 0x1c300000
	s_addc_u32 s5, s87, 0
	v_writelane_b32 v255, s4, 3
	v_readlane_b32 s7, v253, 3
	s_mov_b64 s[6:7], s[20:21]
	v_writelane_b32 v255, s5, 4
	s_and_b64 s[4:5], s[20:21], exec
	s_cselect_b32 s26, 8, 0
	s_add_u32 s4, s86, 0x1f000000
	s_addc_u32 s5, s87, 0
	v_writelane_b32 v255, s4, 5
	s_mov_b32 s2, s52
	v_readlane_b32 s9, v253, 5
	v_writelane_b32 v255, s5, 6
	s_add_u32 s4, s86, 0x1f400000
	s_addc_u32 s5, s87, 0
	v_writelane_b32 v255, s4, 7
	v_readlane_b32 s10, v253, 6
	v_readlane_b32 s11, v253, 7
	v_writelane_b32 v255, s5, 8
	s_add_u32 s4, s86, 0x1f600000
	s_addc_u32 s5, s87, 0
	v_writelane_b32 v255, s4, 9
	v_readlane_b32 s12, v253, 8
	v_readlane_b32 s13, v253, 9
	v_writelane_b32 v255, s5, 10
	s_add_u32 s4, s86, 0x1f780000
	s_addc_u32 s5, s87, 0
	v_writelane_b32 v255, s4, 11
	v_readlane_b32 s14, v253, 10
	v_readlane_b32 s15, v253, 11
	v_writelane_b32 v255, s5, 12
	s_add_u32 s5, s86, 0x1f980000
	s_addc_u32 s8, s87, 0
	s_mul_i32 s4, s26, 0x9000
	s_add_u32 s4, s5, s4
	v_writelane_b32 v255, s4, 13
	v_writelane_b32 v255, s8, 14
	s_addc_u32 s4, s8, 0
	v_writelane_b32 v255, s4, 15
	v_writelane_b32 v255, s6, 16
	s_and_b64 vcc, exec, s[0:1]
	v_readlane_b32 s16, v253, 12
	v_writelane_b32 v255, s7, 17
	v_readlane_b32 s17, v253, 13
	s_cbranch_vccz .LBB0_98
	s_add_u32 s0, s86, 0x17000000
	s_addc_u32 s1, s87, 0
	v_writelane_b32 v255, s0, 22
	s_nop 1
	v_writelane_b32 v255, s1, 23
	s_add_i32 s0, s3, -1
	s_and_b32 s0, s0, 0xff
	s_cmp_lt_u32 s0, 2
	s_cselect_b64 s[0:1], -1, 0
	s_and_b64 s[0:1], s[6:7], s[0:1]
	s_and_b64 s[0:1], s[0:1], exec
	s_cselect_b32 s0, 0x2000000, 0
	v_writelane_b32 v255, s0, 24
	s_and_b32 s0, s3, 0xef
	s_cmp_lg_u32 s0, 1
	s_cbranch_scc0 .LBB0_99
	s_add_u32 s0, s86, 0x14000000
	s_addc_u32 s1, s87, 0
	v_writelane_b32 v255, s0, 25
	s_nop 1
	v_writelane_b32 v255, s1, 26
	s_add_u32 s0, s86, 0x19000000
	s_addc_u32 s1, s87, 0
	v_writelane_b32 v255, s0, 27
	s_nop 1
	v_writelane_b32 v255, s1, 28
	v_readlane_b32 s0, v254, 63
	s_cmp_lt_i32 s0, 15
	v_writelane_b32 v255, s5, 29
	s_cbranch_scc1 .LBB0_100
	s_and_b32 s8, 0xffff, s0
	s_cmp_gt_i32 s8, 17
	s_cbranch_scc0 .LBB0_101
	s_cmp_lg_u32 s8, 18
	s_mov_b64 s[4:5], -1
	s_cselect_b64 s[0:1], -1, 0
	s_cbranch_execz .LBB0_102
	s_branch .LBB0_103
